# grid barrier: the XCD leader does not wait for its own release atomic before leaving the barrier
# speedup vs baseline: 1.0056x; 1.0021x over previous
.LBB0_257:
	s_or_b64 exec, exec, s[6:7]
.LBB0_258:
	s_or_b64 exec, exec, s[0:1]
	s_waitcnt lgkmcnt(0)
	s_barrier

.LBB0_352:
	s_or_b64 exec, exec, s[6:7]
.LBB0_353:
	s_or_b64 exec, exec, s[0:1]
	s_waitcnt lgkmcnt(0)
	s_barrier

.LBB0_478:
	s_or_b64 exec, exec, s[6:7]
.LBB0_479:
	s_or_b64 exec, exec, s[0:1]
	s_waitcnt lgkmcnt(0)
	s_barrier

.LBB0_546:
	s_or_b64 exec, exec, s[6:7]
.LBB0_547:
	s_or_b64 exec, exec, s[0:1]
	s_waitcnt lgkmcnt(0)
	s_barrier

.LBB0_746:
	s_or_b64 exec, exec, s[6:7]
.LBB0_747:
	s_or_b64 exec, exec, s[0:1]
	s_waitcnt lgkmcnt(0)
	s_barrier
